# drop vmcnt(0) drain at GEMM unit start so epilogue stores overlap next units first phases
# baseline (speedup 1.0000x reference)
; __device__ __forceinline__ void gemm_phase(const int bid, const int nblk, LAS unsigned char* lds, const int garg, const int chunk, const Params& p) {
;     ...
;         if (!has_next) break;
; #pragma unroll
;         for (int a = 0; a < 2; ++a)
; #pragma unroll
;             for (int b = 0; b < 2; ++b)
; #pragma unroll
;                 for (int m = 0; m < 4; ++m)
; #pragma unroll
;                     for (int n = 0; n < 2; ++n) acc[a][b][m][n] = (f32x4){0.f, 0.f, 0.f, 0.f};
;         cur = nxt; cA = nA; cB = nB; ++ui;
.LBB0_439:
	v_readlane_b32 s10, v254, 62
	v_readlane_b32 s11, v254, 63
	s_andn2_b64 vcc, exec, s[10:11]
	s_cbranch_vccnz .LBB0_442
	s_add_u32 s2, s2, 0x80
	s_addc_u32 s3, s3, 0
	s_add_u32 s14, s8, 0x100
	v_mov_b32_e32 v126, 0
	s_addc_u32 s15, s9, 0
	s_mov_b32 s8, 0
	v_mov_b32_e32 v127, v126
	v_mov_b32_e32 v128, v126
	v_mov_b32_e32 v129, v126
	v_mov_b32_e32 v78, v126
	v_mov_b32_e32 v79, v126
	v_mov_b32_e32 v80, v126
	v_mov_b32_e32 v81, v126
	v_mov_b32_e32 v62, v126
	v_mov_b32_e32 v63, v126
	v_mov_b32_e32 v64, v126
	v_mov_b32_e32 v65, v126
	v_mov_b32_e32 v14, v126
	v_mov_b32_e32 v15, v126
	v_mov_b32_e32 v16, v126
	v_mov_b32_e32 v17, v126
	v_mov_b32_e32 v0, v126
	v_mov_b32_e32 v1, v126
	v_mov_b32_e32 v2, v126
	v_mov_b32_e32 v3, v126
	v_mov_b32_e32 v4, v126
	v_mov_b32_e32 v5, v126
	v_mov_b32_e32 v6, v126
	v_mov_b32_e32 v7, v126
	v_mov_b32_e32 v22, v126
	v_mov_b32_e32 v23, v126
	v_mov_b32_e32 v24, v126
	v_mov_b32_e32 v25, v126
	v_mov_b32_e32 v26, v126
	v_mov_b32_e32 v27, v126
	v_mov_b32_e32 v28, v126
	v_mov_b32_e32 v29, v126
	v_mov_b32_e32 v38, v126
	v_mov_b32_e32 v39, v126
	v_mov_b32_e32 v40, v126
	v_mov_b32_e32 v41, v126
	v_mov_b32_e32 v42, v126
	v_mov_b32_e32 v43, v126
	v_mov_b32_e32 v44, v126
	v_mov_b32_e32 v45, v126
	v_mov_b32_e32 v54, v126
	v_mov_b32_e32 v55, v126
	v_mov_b32_e32 v56, v126
	v_mov_b32_e32 v57, v126
	v_mov_b32_e32 v58, v126
	v_mov_b32_e32 v59, v126
	v_mov_b32_e32 v60, v126
	v_mov_b32_e32 v61, v126
	v_mov_b32_e32 v18, v126
	v_mov_b32_e32 v19, v126
	v_mov_b32_e32 v20, v126
	v_mov_b32_e32 v21, v126
	v_mov_b32_e32 v30, v126
	v_mov_b32_e32 v31, v126
	v_mov_b32_e32 v32, v126
	v_mov_b32_e32 v33, v126
	v_mov_b32_e32 v34, v126
	v_mov_b32_e32 v35, v126
	v_mov_b32_e32 v36, v126
	v_mov_b32_e32 v37, v126
	v_mov_b32_e32 v46, v126
	v_mov_b32_e32 v47, v126
	v_mov_b32_e32 v48, v126
	v_mov_b32_e32 v49, v126
	v_mov_b32_e32 v50, v126
	v_mov_b32_e32 v51, v126
	v_mov_b32_e32 v52, v126
	v_mov_b32_e32 v53, v126
	v_mov_b32_e32 v66, v126
	v_mov_b32_e32 v67, v126
	v_mov_b32_e32 v68, v126
	v_mov_b32_e32 v69, v126
	v_mov_b32_e32 v70, v126
	v_mov_b32_e32 v71, v126
	v_mov_b32_e32 v72, v126
	v_mov_b32_e32 v73, v126
	v_mov_b32_e32 v74, v126
	v_mov_b32_e32 v75, v126
	v_mov_b32_e32 v76, v126
	v_mov_b32_e32 v77, v126
	v_mov_b32_e32 v86, v126
	v_mov_b32_e32 v87, v126
	v_mov_b32_e32 v88, v126
	v_mov_b32_e32 v89, v126
	v_mov_b32_e32 v90, v126
	v_mov_b32_e32 v91, v126
	v_mov_b32_e32 v92, v126
	v_mov_b32_e32 v93, v126
	v_mov_b32_e32 v102, v126
	v_mov_b32_e32 v103, v126
	v_mov_b32_e32 v104, v126
	v_mov_b32_e32 v105, v126
	v_mov_b32_e32 v106, v126
	v_mov_b32_e32 v107, v126
	v_mov_b32_e32 v108, v126
	v_mov_b32_e32 v109, v126
	v_mov_b32_e32 v118, v126
	v_mov_b32_e32 v119, v126
	v_mov_b32_e32 v120, v126
	v_mov_b32_e32 v121, v126
	v_mov_b32_e32 v122, v126
	v_mov_b32_e32 v123, v126
	v_mov_b32_e32 v124, v126
	v_mov_b32_e32 v125, v126
	v_mov_b32_e32 v82, v126
	v_mov_b32_e32 v83, v126
	v_mov_b32_e32 v84, v126
	v_mov_b32_e32 v85, v126
	v_mov_b32_e32 v94, v126
	v_mov_b32_e32 v95, v126
	v_mov_b32_e32 v96, v126
	v_mov_b32_e32 v97, v126
	v_mov_b32_e32 v98, v126
	v_mov_b32_e32 v99, v126
	v_mov_b32_e32 v100, v126
	v_mov_b32_e32 v101, v126
	v_mov_b32_e32 v110, v126
	v_mov_b32_e32 v111, v126
	v_mov_b32_e32 v112, v126
	v_mov_b32_e32 v113, v126
	v_mov_b32_e32 v114, v126
	v_mov_b32_e32 v115, v126
	v_mov_b32_e32 v116, v126
	v_mov_b32_e32 v117, v126
	v_mov_b32_e32 v130, v126
	v_mov_b32_e32 v131, v126
	v_mov_b32_e32 v132, v126
	v_mov_b32_e32 v133, v126
